# v76 + filter output layer: both 8-load W4 batches of an iteration issued together (second batch into fresh registers), counted waits adjusted
# speedup vs baseline: 1.0017x; 1.0017x over previous
; #define GAS __attribute__((address_space(1)))
; __device__ __forceinline__ unsigned pk2(float lo, float hi) { unsigned r; asm("v_cvt_pk_bf16_f32 %0, %1, %2" : "=v"(r) : "v"(lo), "v"(hi)); return r; }
; __device__ __forceinline__ void pro_a(Frame& F, CArgs a, unsigned long long& tm_acc) {
;     ...
;                 for (int n = 0; n < 8; ++n) {
;                     f32x4 acc[4];
; #pragma unroll
;                     for (int m = 0; m < 4; ++m) acc[m] = (f32x4){0.f, 0.f, 0.f, 0.f};
; #pragma unroll
;                     for (int ks = 0; ks < 2; ++ks) {
;                         float wv[8];
; #pragma unroll
;                         for (int j = 0; j < 8; ++j) wv[j] = w4[(size_t)(32 * ks + 8 * g + j) * 1024 + 16 * n];
;                         const u32x4 pw = (u32x4){pk2(wv[0], wv[1]), pk2(wv[2], wv[3]), pk2(wv[4], wv[5]), pk2(wv[6], wv[7])};
;                         const bf16x8 bfr = __builtin_bit_cast(bf16x8, pw);
; #pragma unroll
;                         for (int m = 0; m < 4; ++m) acc[m] = __builtin_amdgcn_mfma_f32_16x16x32_bf16(af[m][ks], bfr, acc[m], 0, 0, 0);
;                     }
;                     const int ch = (c0 & 511) + 16 * n + r;
;                     const float adelta = fabsf(min_decay + (float)ch * ((max_decay - min_decay) / 511.0f));
;                     GAS bf16_t* dst = isc ? krc + ((size_t)l * 512 + ch) * 512 : krg + ((size_t)l * 512 + ch) * 4096;
;                     if (p0 == 0 && !bwd && g == 0 && n < 8) dst[0] = (bf16_t)0;
.LBB0_248:
	v_lshl_add_u64 v[46:47], v[58:59], 0, s[16:17]
	v_add_co_u32_e32 v34, vcc, 0x1000, v46
	s_nop 1
	v_addc_co_u32_e32 v35, vcc, 0, v47, vcc
	v_add_co_u32_e32 v36, vcc, 0x2000, v46
	s_nop 1
	v_addc_co_u32_e32 v37, vcc, 0, v47, vcc
	v_add_co_u32_e32 v38, vcc, 0x3000, v46
	s_nop 1
	v_addc_co_u32_e32 v39, vcc, 0, v47, vcc
	v_add_co_u32_e32 v40, vcc, 0x4000, v46
	s_nop 1
	v_addc_co_u32_e32 v41, vcc, 0, v47, vcc
	v_add_co_u32_e32 v42, vcc, 0x5000, v46
	s_nop 1
	v_addc_co_u32_e32 v43, vcc, 0, v47, vcc
	v_add_co_u32_e32 v44, vcc, 0x6000, v46
	s_nop 1
	v_addc_co_u32_e32 v45, vcc, 0, v47, vcc
	v_add_co_u32_e32 v48, vcc, 0x7000, v46
	s_nop 1
	v_addc_co_u32_e32 v49, vcc, 0, v47, vcc
	global_load_dword v60, v[34:35], off
	global_load_dword v61, v[36:37], off
	global_load_dword v62, v[38:39], off
	global_load_dword v63, v[40:41], off
	global_load_dword v93, v[42:43], off
	global_load_dword v94, v[44:45], off
	global_load_dword v95, v[48:49], off
	global_load_dword v96, v[46:47], off
	s_mov_b64 s[100:101], 0x20000
	v_lshl_add_u64 v[110:111], v[46:47], 0, s[100:101]
	global_load_dword v102, v[110:111], off
	s_add_u32 s100, s100, 0x1000
	v_lshl_add_u64 v[112:113], v[46:47], 0, s[100:101]
	global_load_dword v103, v[112:113], off
	s_add_u32 s100, s100, 0x1000
	v_lshl_add_u64 v[114:115], v[46:47], 0, s[100:101]
	global_load_dword v104, v[114:115], off
	s_add_u32 s100, s100, 0x1000
	v_lshl_add_u64 v[116:117], v[46:47], 0, s[100:101]
	global_load_dword v105, v[116:117], off
	s_add_u32 s100, s100, 0x1000
	v_lshl_add_u64 v[118:119], v[46:47], 0, s[100:101]
	global_load_dword v106, v[118:119], off
	s_add_u32 s100, s100, 0x1000
	v_lshl_add_u64 v[120:121], v[46:47], 0, s[100:101]
	global_load_dword v107, v[120:121], off
	s_add_u32 s100, s100, 0x1000
	v_lshl_add_u64 v[122:123], v[46:47], 0, s[100:101]
	global_load_dword v108, v[122:123], off
	s_add_u32 s100, s100, 0x1000
	v_lshl_add_u64 v[124:125], v[46:47], 0, s[100:101]
	global_load_dword v109, v[124:125], off
	v_add_co_u32_e32 v48, vcc, 0x20000, v46
	s_waitcnt vmcnt(13)
	v_cvt_pk_bf16_f32 v35, v61, v62
	s_nop 0
	v_addc_co_u32_e32 v49, vcc, 0, v47, vcc
	v_add_co_u32_e32 v82, vcc, 0x21000, v46
	s_waitcnt vmcnt(11)
	v_cvt_pk_bf16_f32 v36, v63, v93
	s_waitcnt vmcnt(8)
	v_cvt_pk_bf16_f32 v34, v96, v60
	v_cvt_pk_bf16_f32 v37, v94, v95
	v_addc_co_u32_e32 v83, vcc, 0, v47, vcc
	v_add_co_u32_e32 v84, vcc, 0x22000, v46
	v_mfma_f32_16x16x32_bf16 v[38:41], v[2:5], v[34:37], 0
	s_nop 0
	v_addc_co_u32_e32 v85, vcc, 0, v47, vcc
	v_add_co_u32_e32 v86, vcc, 0x23000, v46
	v_mfma_f32_16x16x32_bf16 v[42:45], v[10:13], v[34:37], 0
	s_nop 0
	v_addc_co_u32_e32 v87, vcc, 0, v47, vcc
	v_add_co_u32_e32 v88, vcc, 0x24000, v46
	v_mfma_f32_16x16x32_bf16 v[60:63], v[18:21], v[34:37], 0
	s_nop 0
	v_addc_co_u32_e32 v89, vcc, 0, v47, vcc
	v_add_co_u32_e32 v90, vcc, 0x25000, v46
	v_mfma_f32_16x16x32_bf16 v[34:37], v[26:29], v[34:37], 0
	s_nop 0
	v_addc_co_u32_e32 v91, vcc, 0, v47, vcc
	v_add_co_u32_e32 v92, vcc, 0x26000, v46
	s_nop 1
	v_addc_co_u32_e32 v93, vcc, 0, v47, vcc
	v_add_co_u32_e32 v46, vcc, 0x27000, v46
	s_nop 1
	v_addc_co_u32_e32 v47, vcc, 0, v47, vcc
	s_waitcnt vmcnt(6)
	v_cvt_pk_bf16_f32 v82, v102, v103
	s_waitcnt vmcnt(4)
	v_cvt_pk_bf16_f32 v83, v104, v105
	s_waitcnt vmcnt(2)
	v_cvt_pk_bf16_f32 v84, v106, v107
	s_waitcnt vmcnt(0)
	v_cvt_pk_bf16_f32 v85, v108, v109
	s_nop 0
	v_mfma_f32_16x16x32_bf16 v[46:49], v[6:9], v[82:85], v[38:41]
	v_mfma_f32_16x16x32_bf16 v[42:45], v[14:17], v[82:85], v[42:45]
	v_mfma_f32_16x16x32_bf16 v[38:41], v[22:25], v[82:85], v[60:63]
	v_mfma_f32_16x16x32_bf16 v[34:37], v[30:33], v[82:85], v[34:37]
	s_nop 1
	v_lshlrev_b32_e32 v60, s22, v79
	v_or_b32_e32 v60, s24, v60
	v_mov_b32_e32 v61, s23
	v_lshl_add_u64 v[60:61], v[60:61], 1, s[14:15]
	s_and_saveexec_b64 s[6:7], s[12:13]
	s_cbranch_execz .LBB0_250
	global_store_short v[60:61], v57, off
